# p1: first K-step after a tile epilogue waits vmcnt(24) instead of vmcnt(8) so the 16 output stores are not forced to drain before the next tile starts
# baseline (speedup 1.0000x reference)
; #define PG8_STAGE(bufoff, gbase, voff) do { _Pragma("unroll") for (int _i = 0; _i < 2; ++_i) \
;         __builtin_amdgcn_global_load_lds((const unsigned*)((const char*)(gbase) + (voff)[_i]), (LAS unsigned*)(lds + (bufoff) + ldsw + _i * 8192), 16, 0, 0); } while (0)
; #define PG8_WAIT_V(n) asm volatile("s_waitcnt vmcnt(" #n ")" ::: "memory")
; #define PG8_BAR __builtin_amdgcn_s_barrier()
;     DI bool next(int i, Unit& u) const {
;         const long L = (long)i * G + c; if (L >= nwg) return false;
;         int wgid = (int)L; { const int q = nwg / NXCD, r = nwg % NXCD, xcd = wgid % NXCD, off = wgid / NXCD; wgid = (xcd < r ? xcd * (q + 1) : r * (q + 1) + (xcd - r) * q) + off; }
;         const int nig = WGM * nN, gid = wgid / nig, fm = gid * WGM, gsz = (nM - fm) < WGM ? (nM - fm) : WGM;
;         u.pm = fm + ((wgid % nig) % gsz); u.pn = (wgid % nig) / gsz; return true;
; template <class Epi>
; DI void gemm_phase(LAS unsigned char* lds, const Gemm g, const StaticOrder& S, const Epi& E) {
;     ...
;     PG8_STAGE(PG8_SB(0, 0), cB, voffB); PG8_STAGE(PG8_SA(0, 0), cA, voffA); PG8_STAGE(PG8_SB(0, 1), cB + hstepB, voffB); PG8_STAGE(PG8_SA(0, 1), cA + hstepA, voffA);
;     if (wr == 1) PG8_BAR;
;     PG8_WAIT_V(4); PG8_BAR;
;     PG8_STAGE(PG8_SB(1, 0), cB + kstep, voffB); PG8_STAGE(PG8_SA(1, 0), cA + kstep, voffA); PG8_STAGE(PG8_SB(1, 1), cB + hstepB + kstep, voffB);
;     PG8_WAIT_V(6); PG8_BAR;
;     for (;;) {
;         const bool has_next = S.next(ui + 1, nxt);
;         const char* nA = has_next ? (const char*)g.A + (size_t)nxt.pm * tstepA : cA; const char* nB = has_next ? (const char*)g.Bt + (size_t)nxt.pn * tstepB : cB;
.LBB0_109:
	s_lshl_b32 s0, s4, 5
	s_mov_b64 s[4:5], 0x80
	s_and_b32 s17, s0, 0x60
	s_add_i32 m0, s9, 0x18000
	v_lshl_add_u64 v[6:7], v[6:7], 0, s[4:5]
	s_lshl_b32 s16, s3, 13
	s_lshl_b32 s46, s17, 7
	s_waitcnt vmcnt(2)
	s_barrier
	global_load_lds_dwordx4 v[6:7], off
	v_lshl_add_u64 v[4:5], v[4:5], 0, s[4:5]
	s_add_i32 m0, s9, 0x1a000
	s_add_i32 s71, s9, 0x8000
	s_add_i32 s72, s9, 0xa000
	global_load_lds_dwordx4 v[4:5], off
	v_lshl_add_u64 v[2:3], v[2:3], 0, s[4:5]
	s_mov_b32 m0, s71
	s_add_u32 s0, s54, 0x80080
	global_load_lds_dwordx4 v[2:3], off
	v_lshl_add_u64 v[0:1], v[0:1], 0, s[4:5]
	s_mov_b32 m0, s72
	s_addc_u32 s1, s55, 0
	global_load_lds_dwordx4 v[0:1], off
	s_add_i32 m0, s9, 0x1c000
	v_lshl_add_u64 v[0:1], s[0:1], 0, v[132:133]
	global_load_lds_dwordx4 v[0:1], off
	v_lshl_add_u64 v[0:1], s[0:1], 0, v[128:129]
	s_add_i32 m0, s9, 0x1e000
	s_add_i32 s75, 0, 0x10000
	global_load_lds_dwordx4 v[0:1], off
	v_lshrrev_b32_e32 v1, 1, v9
	v_and_b32_e32 v1, 24, v1
	v_and_b32_e32 v0, 15, v9
	v_lshlrev_b32_e32 v2, 1, v1
	v_lshl_or_b32 v144, s3, 6, v0
	v_lshl_or_b32 v0, v0, 6, v2
	v_lshlrev_b32_e32 v2, 2, v9
	v_and_b32_e32 v2, 32, v2
	v_bitop3_b32 v3, v0, s16, v2 bitop3:0xde
	v_bitop3_b32 v145, v0, s46, v2 bitop3:0xde
	v_lshlrev_b32_e32 v0, 15, v13
	v_and_b32_e32 v0, 0xffff0000, v0
	v_or_b32_e32 v146, s17, v1
	v_lshl_add_u32 v0, v12, 12, v0
	v_and_b32_e32 v1, 1, v13
	v_lshl_or_b32 v0, v1, 6, v0
	v_lshl_add_u32 v136, v14, 1, v0
	v_lshlrev_b32_e32 v0, 15, v8
	v_and_b32_e32 v0, 0xffff0000, v0
	s_waitcnt vmcnt(6)
	v_lshl_add_u32 v0, v10, 12, v0
	v_and_b32_e32 v1, 1, v8
	v_lshl_or_b32 v0, v1, 6, v0
	s_add_i32 s76, 0, 0x14000
	s_sext_i32_i16 s78, s2
	s_ashr_i32 s73, s10, 31
	s_mov_b32 s74, s10
	v_mov_b32_e32 v137, v133
	v_lshl_add_u32 v138, v11, 1, v0
	v_mov_b32_e32 v139, v133
	v_mov_b64_e32 v[140:141], 0x1d80
	v_mov_b64_e32 v[142:143], 0x1d7f
	v_add_u32_e32 v147, s75, v145
	v_add_u32_e32 v148, 0, v3
	v_add_u32_e32 v149, s76, v145
	s_movk_i32 s77, 0x7600
	s_barrier
	s_mov_b32 s98, 0
.LBB0_110:
	s_mov_b32 s99, s98
	s_add_i32 s70, s70, 1
	s_mul_i32 s0, s70, s73
	s_mul_hi_u32 s1, s70, s74
	s_add_i32 s1, s1, s0
	s_mul_i32 s0, s70, s74
	s_add_u32 s48, s0, s6
	s_addc_u32 s49, s1, s59
	v_cmp_gt_i64_e64 s[2:3], s[48:49], v[142:143]
	s_and_b64 vcc, exec, s[2:3]
	s_cbranch_vccnz .LBB0_112
	s_ashr_i32 s0, s48, 31
	s_lshr_b32 s0, s0, 29
	s_add_i32 s0, s48, s0
	s_ashr_i32 s1, s0, 3
	s_and_b32 s0, s0, -8
	s_sub_i32 s0, s48, s0
	s_cmp_lt_i32 s0, 0
	s_cselect_b32 s16, s60, 0x3b0
	s_mul_i32 s0, s16, s0
	s_add_i32 s0, s0, s1
	s_mul_hi_i32 s1, s0, 0x22b63cbf
	s_lshr_b32 s16, s1, 31
	s_ashr_i32 s1, s1, 6
	s_add_i32 s1, s1, s16
	s_lshl_b32 s17, s1, 3
	s_sub_i32 s16, 0x80, s17
	s_min_i32 s46, s16, 8
	s_abs_i32 s16, s46
	v_cvt_f32_u32_e32 v0, s16
	s_sub_i32 s50, 0, s16
	s_mulk_i32 s1, 0x1d8
	s_sub_i32 s0, s0, s1
	v_rcp_iflag_f32_e32 v0, v0
	s_abs_i32 s1, s0
	s_xor_b32 s47, s0, s46
	s_ashr_i32 s47, s47, 31
	v_mul_f32_e32 v0, 0x4f7ffffe, v0
	v_cvt_u32_f32_e32 v0, v0
	s_nop 0
	v_readfirstlane_b32 s51, v0
	s_mul_i32 s50, s50, s51
	s_mul_hi_u32 s50, s51, s50
	s_add_i32 s51, s51, s50
	s_mul_hi_u32 s50, s1, s51
	s_mul_i32 s51, s50, s16
	s_sub_i32 s1, s1, s51
	s_add_i32 s56, s50, 1
	s_sub_i32 s51, s1, s16
	s_cmp_ge_u32 s1, s16
	s_cselect_b32 s50, s56, s50
	s_cselect_b32 s1, s51, s1
	s_add_i32 s51, s50, 1
	s_cmp_ge_u32 s1, s16
	s_cselect_b32 s1, s51, s50
	s_xor_b32 s1, s1, s47
	s_sub_i32 s16, s1, s47
	s_mul_i32 s1, s16, s46
	s_sub_i32 s0, s0, s1
	s_add_i32 s46, s0, s17

; #define PG8_STAGE(bufoff, gbase, voff) do { _Pragma("unroll") for (int _i = 0; _i < 2; ++_i) \
;         __builtin_amdgcn_global_load_lds((const unsigned*)((const char*)(gbase) + (voff)[_i]), (LAS unsigned*)(lds + (bufoff) + ldsw + _i * 8192), 16, 0, 0); } while (0)
; #define PG8_LDA(dst, b, h) do { _Pragma("unroll") for (int m = 0; m < 4; ++m) _Pragma("unroll") for (int k = 0; k < 2; ++k) dst[m][k] = *(const LAS bf16x8*)(lds + PG8_SA(b, h) + aoff + m * 2048 + k * 1024); } while (0)
; #define PG8_LDB(dst, b, h) do { _Pragma("unroll") for (int n = 0; n < 2; ++n) _Pragma("unroll") for (int k = 0; k < 2; ++k) dst[n][k] = *(const LAS bf16x8*)(lds + PG8_SB(b, h) + boff + n * 2048 + k * 1024); } while (0)
; #define PG8_MMA(ai, bj, At, Bt) do { __builtin_amdgcn_s_setprio(1); _Pragma("unroll") for (int m = 0; m < 4; ++m) _Pragma("unroll") for (int n = 0; n < 2; ++n) _Pragma("unroll") for (int k = 0; k < 2; ++k) \
;         acc[ai][bj][m][n] = __builtin_amdgcn_mfma_f32_16x16x32_bf16(Bt[n][k], At[m][k], acc[ai][bj][m][n], 0, 0, 0); __builtin_amdgcn_s_setprio(0); } while (0)
; #define PG8_WAIT_V(n) asm volatile("s_waitcnt vmcnt(" #n ")" ::: "memory")
; template <class Epi>
; DI void gemm_phase(LAS unsigned char* lds, const Gemm g, const StaticOrder& S, const Epi& E) {
;     ...
;         for (int t = 0; t < nt; t += 2) {
;             const bool last = (t == nt - 2);
;             const char* a1 = cA + (size_t)(t + 1) * kstep;
;             const char* a2 = last ? nA : cA + (size_t)(t + 2) * kstep; const char* b2 = last ? nB : cB + (size_t)(t + 2) * kstep;
;             const char* a3 = a2 + kstep; const char* b3 = b2 + kstep;
;             if constexpr (Epi::HAS_MID) { if (t == Epi::MID_T) E.mid(acc, cur, wr, wc, fr, fq); }
;             PG8_LDB(B0, 0, 0); PG8_SCHED; PG8_LDA(At, 0, 0); PG8_STAGE(PG8_SA(1, 1), a1 + hstepA, voffA);
;             PG8_WAIT_L(8); PG8_BAR; PG8_WAIT_L(0); PG8_MMA(0, 0, At, B0); PG8_BAR; PG8_SCHED;
;             PG8_LDB(B1, 0, 1); PG8_STAGE(PG8_SB(0, 0), b2, voffB);
;             PG8_BAR; PG8_WAIT_L(0); PG8_MMA(0, 1, At, B1); PG8_BAR;
;             PG8_LDA(At, 0, 1); PG8_STAGE(PG8_SA(0, 0), a2, voffA);
;             PG8_BAR; PG8_WAIT_L(0); PG8_MMA(1, 0, At, B0); PG8_BAR; PG8_SCHED;
;             PG8_STAGE(PG8_SB(0, 1), b2 + hstepB, voffB);
;             PG8_WAIT_V(6); PG8_BAR; PG8_MMA(1, 1, At, B1); PG8_BAR;
.LBB0_113:
	ds_read_b128 v[150:153], v147
	ds_read_b128 v[154:157], v147 offset:1024
	ds_read_b128 v[158:161], v147 offset:2048
	ds_read_b128 v[162:165], v147 offset:3072
	s_add_u32 s0, s52, 0xfff80080
	s_addc_u32 s1, s53, -1
	s_cmp_eq_u32 s83, 28
	s_cselect_b32 s57, s47, s1
	s_cselect_b32 s56, s79, s0
	s_cselect_b32 s55, s17, s82
	s_cselect_b32 s54, s80, s81
	ds_read_b128 v[166:169], v148
	ds_read_b128 v[174:177], v148 offset:1024
	ds_read_b128 v[178:181], v148 offset:2048
	ds_read_b128 v[182:185], v148 offset:3072
	ds_read_b128 v[186:189], v148 offset:4096
	ds_read_b128 v[190:193], v148 offset:5120
	ds_read_b128 v[194:197], v148 offset:6144
	ds_read_b128 v[198:201], v148 offset:7168
	s_waitcnt lgkmcnt(11)
	ds_read_b128 v[202:205], v149
	ds_read_b128 v[206:209], v149 offset:1024
	ds_read_b128 v[210:213], v149 offset:2048
	ds_read_b128 v[216:219], v149 offset:3072
	v_lshl_add_u64 v[238:239], s[52:53], 0, v[136:137]
	s_add_i32 m0, s9, 0xc000
	s_nop 0
	global_load_lds_dwordx4 v[238:239], off
	v_lshl_add_u64 v[238:239], s[52:53], 0, v[138:139]
	s_add_i32 m0, s9, 0xe000
	s_nop 0
	global_load_lds_dwordx4 v[238:239], off
	s_waitcnt lgkmcnt(0)
	s_cmp_eq_u32 s99, 0
	s_cbranch_scc1 .Lp1w1n
	s_waitcnt vmcnt(24)
	s_branch .Lp1w1d
.Lp1w1n:
	s_waitcnt vmcnt(8)
.Lp1w1d:
	s_barrier
	v_mfma_f32_16x16x32_bf16 v[124:127], v[150:153], v[166:169], v[124:127]
	v_mfma_f32_16x16x32_bf16 v[120:123], v[158:161], v[166:169], v[120:123]
	v_mfma_f32_16x16x32_bf16 v[116:119], v[150:153], v[178:181], v[116:119]
	v_mfma_f32_16x16x32_bf16 v[112:115], v[158:161], v[178:181], v[112:115]
	v_mfma_f32_16x16x32_bf16 v[100:103], v[150:153], v[186:189], v[100:103]
	v_mfma_f32_16x16x32_bf16 v[96:99], v[158:161], v[186:189], v[96:99]
	v_mfma_f32_16x16x32_bf16 v[84:87], v[150:153], v[194:197], v[84:87]
	v_mfma_f32_16x16x32_bf16 v[80:83], v[158:161], v[194:197], v[80:83]
	v_mfma_f32_16x16x32_bf16 v[124:127], v[154:157], v[174:177], v[124:127]
	v_mfma_f32_16x16x32_bf16 v[120:123], v[162:165], v[174:177], v[120:123]
	v_mfma_f32_16x16x32_bf16 v[116:119], v[154:157], v[182:185], v[116:119]
	v_mfma_f32_16x16x32_bf16 v[112:115], v[162:165], v[182:185], v[112:115]
	v_mfma_f32_16x16x32_bf16 v[100:103], v[154:157], v[190:193], v[100:103]
	v_mfma_f32_16x16x32_bf16 v[96:99], v[162:165], v[190:193], v[96:99]
	v_mfma_f32_16x16x32_bf16 v[84:87], v[154:157], v[198:201], v[84:87]
	v_mfma_f32_16x16x32_bf16 v[80:83], v[162:165], v[198:201], v[80:83]
	v_mfma_f32_16x16x32_bf16 v[108:111], v[202:205], v[166:169], v[108:111]
	v_mfma_f32_16x16x32_bf16 v[104:107], v[210:213], v[166:169], v[104:107]
	v_mfma_f32_16x16x32_bf16 v[92:95], v[202:205], v[178:181], v[92:95]
	v_mfma_f32_16x16x32_bf16 v[88:91], v[210:213], v[178:181], v[88:91]
	v_mfma_f32_16x16x32_bf16 v[76:79], v[202:205], v[186:189], v[76:79]
	v_mfma_f32_16x16x32_bf16 v[72:75], v[210:213], v[186:189], v[72:75]
	v_mfma_f32_16x16x32_bf16 v[68:71], v[202:205], v[194:197], v[68:71]
	v_mfma_f32_16x16x32_bf16 v[64:67], v[210:213], v[194:197], v[64:67]
	v_mfma_f32_16x16x32_bf16 v[108:111], v[206:209], v[174:177], v[108:111]
	v_mfma_f32_16x16x32_bf16 v[104:107], v[216:219], v[174:177], v[104:107]
	v_mfma_f32_16x16x32_bf16 v[92:95], v[206:209], v[182:185], v[92:95]
	v_mfma_f32_16x16x32_bf16 v[88:91], v[216:219], v[182:185], v[88:91]
	v_mfma_f32_16x16x32_bf16 v[76:79], v[206:209], v[190:193], v[76:79]
	v_mfma_f32_16x16x32_bf16 v[72:75], v[216:219], v[190:193], v[72:75]
	v_mfma_f32_16x16x32_bf16 v[68:71], v[206:209], v[198:201], v[68:71]
	v_mfma_f32_16x16x32_bf16 v[64:67], v[216:219], v[198:201], v[64:67]
	s_barrier
	ds_read_b128 v[166:169], v148 offset:16384
	ds_read_b128 v[174:177], v148 offset:17408
	ds_read_b128 v[178:181], v148 offset:18432
	ds_read_b128 v[182:185], v148 offset:19456
	ds_read_b128 v[186:189], v148 offset:20480
	ds_read_b128 v[190:193], v148 offset:21504
	ds_read_b128 v[194:197], v148 offset:22528
	ds_read_b128 v[198:201], v148 offset:23552
	s_add_i32 s0, s75, s58
	v_lshl_add_u64 v[170:171], s[54:55], 0, v[132:133]
	s_mov_b32 m0, s0
	s_nop 0
	global_load_lds_dwordx4 v[170:171], off
	v_lshl_add_u64 v[220:221], s[54:55], 0, v[128:129]
	s_add_i32 m0, s0, 0x2000
	s_nop 0
	global_load_lds_dwordx4 v[220:221], off
	v_lshl_add_u64 v[222:223], s[56:57], 0, v[134:135]
	s_mov_b32 m0, s9
	s_nop 0
	global_load_lds_dwordx4 v[222:223], off
	v_lshl_add_u64 v[224:225], s[56:57], 0, v[130:131]
	s_mov_b32 m0, s61
	s_nop 0
	global_load_lds_dwordx4 v[224:225], off
	s_add_u32 s0, s54, 0x80000
	s_addc_u32 s1, s55, 0
	s_add_i32 s84, s76, s58
	v_lshl_add_u64 v[238:239], s[0:1], 0, v[132:133]
	s_mov_b32 m0, s84
	s_nop 0
	global_load_lds_dwordx4 v[238:239], off
	v_lshl_add_u64 v[238:239], s[0:1], 0, v[128:129]
	s_add_i32 m0, s84, 0x2000
	s_nop 0
	global_load_lds_dwordx4 v[238:239], off
	s_waitcnt lgkmcnt(0)
	s_cmp_eq_u32 s99, 0
	s_cbranch_scc1 .Lp1w2n
	s_waitcnt vmcnt(24)
	s_branch .Lp1w2d

; #define PG8_STAGE(bufoff, gbase, voff) do { _Pragma("unroll") for (int _i = 0; _i < 2; ++_i) \
;         __builtin_amdgcn_global_load_lds((const unsigned*)((const char*)(gbase) + (voff)[_i]), (LAS unsigned*)(lds + (bufoff) + ldsw + _i * 8192), 16, 0, 0); } while (0)
; #define PG8_LDA(dst, b, h) do { _Pragma("unroll") for (int m = 0; m < 4; ++m) _Pragma("unroll") for (int k = 0; k < 2; ++k) dst[m][k] = *(const LAS bf16x8*)(lds + PG8_SA(b, h) + aoff + m * 2048 + k * 1024); } while (0)
; #define PG8_LDB(dst, b, h) do { _Pragma("unroll") for (int n = 0; n < 2; ++n) _Pragma("unroll") for (int k = 0; k < 2; ++k) dst[n][k] = *(const LAS bf16x8*)(lds + PG8_SB(b, h) + boff + n * 2048 + k * 1024); } while (0)
; #define PG8_MMA(ai, bj, At, Bt) do { __builtin_amdgcn_s_setprio(1); _Pragma("unroll") for (int m = 0; m < 4; ++m) _Pragma("unroll") for (int n = 0; n < 2; ++n) _Pragma("unroll") for (int k = 0; k < 2; ++k) \
;         acc[ai][bj][m][n] = __builtin_amdgcn_mfma_f32_16x16x32_bf16(Bt[n][k], At[m][k], acc[ai][bj][m][n], 0, 0, 0); __builtin_amdgcn_s_setprio(0); } while (0)
; #define PG8_WAIT_V(n) asm volatile("s_waitcnt vmcnt(" #n ")" ::: "memory")
; #define PG8_WAIT_L(n) asm volatile("s_waitcnt lgkmcnt(" #n ")" ::: "memory")
; #define PG8_BAR __builtin_amdgcn_s_barrier()
; #define PG8_SCHED __builtin_amdgcn_sched_barrier(0)
; template <class Epi>
; DI void gemm_phase(LAS unsigned char* lds, const Gemm g, const StaticOrder& S, const Epi& E) {
;     ...
;             PG8_BAR; PG8_WAIT_L(0); PG8_MMA(1, 0, At, B0); PG8_BAR; PG8_SCHED;
;             PG8_STAGE(PG8_SB(0, 1), b2 + hstepB, voffB);
;             PG8_WAIT_V(6); PG8_BAR; PG8_MMA(1, 1, At, B1); PG8_BAR;
;             PG8_LDB(B0, 1, 0); PG8_SCHED; PG8_LDA(At, 1, 0); PG8_STAGE(PG8_SA(0, 1), a2 + hstepA, voffA);
;             PG8_WAIT_L(8); PG8_BAR; PG8_WAIT_L(0); PG8_MMA(0, 0, At, B0); PG8_BAR; PG8_SCHED;
;             PG8_LDB(B1, 1, 1); PG8_STAGE(PG8_SB(1, 0), b3, voffB);
;             PG8_BAR; PG8_WAIT_L(0); PG8_MMA(0, 1, At, B1); PG8_BAR;
;             PG8_LDA(At, 1, 1); PG8_STAGE(PG8_SA(1, 0), a3, voffA);
;             PG8_BAR; PG8_WAIT_L(0); PG8_MMA(1, 0, At, B0); PG8_BAR; PG8_SCHED;
.Lp1w2d:
	s_barrier
	v_mfma_f32_16x16x32_bf16 v[60:63], v[150:153], v[166:169], v[60:63]
	v_mfma_f32_16x16x32_bf16 v[56:59], v[158:161], v[166:169], v[56:59]
	v_mfma_f32_16x16x32_bf16 v[52:55], v[150:153], v[178:181], v[52:55]
	v_mfma_f32_16x16x32_bf16 v[48:51], v[158:161], v[178:181], v[48:51]
	v_mfma_f32_16x16x32_bf16 v[36:39], v[150:153], v[186:189], v[36:39]
	v_mfma_f32_16x16x32_bf16 v[32:35], v[158:161], v[186:189], v[32:35]
	v_mfma_f32_16x16x32_bf16 v[20:23], v[150:153], v[194:197], v[20:23]
	v_mfma_f32_16x16x32_bf16 v[16:19], v[158:161], v[194:197], v[16:19]
	v_mfma_f32_16x16x32_bf16 v[60:63], v[154:157], v[174:177], v[60:63]
	v_mfma_f32_16x16x32_bf16 v[56:59], v[162:165], v[174:177], v[56:59]
	v_mfma_f32_16x16x32_bf16 v[52:55], v[154:157], v[182:185], v[52:55]
	v_mfma_f32_16x16x32_bf16 v[48:51], v[162:165], v[182:185], v[48:51]
	v_mfma_f32_16x16x32_bf16 v[36:39], v[154:157], v[190:193], v[36:39]
	v_mfma_f32_16x16x32_bf16 v[32:35], v[162:165], v[190:193], v[32:35]
	v_mfma_f32_16x16x32_bf16 v[20:23], v[154:157], v[198:201], v[20:23]
	v_mfma_f32_16x16x32_bf16 v[16:19], v[162:165], v[198:201], v[16:19]
	v_mfma_f32_16x16x32_bf16 v[44:47], v[202:205], v[166:169], v[44:47]
	v_mfma_f32_16x16x32_bf16 v[40:43], v[210:213], v[166:169], v[40:43]
	v_mfma_f32_16x16x32_bf16 v[28:31], v[202:205], v[178:181], v[28:31]
	v_mfma_f32_16x16x32_bf16 v[24:27], v[210:213], v[178:181], v[24:27]
	v_mfma_f32_16x16x32_bf16 v[12:15], v[202:205], v[186:189], v[12:15]
	v_mfma_f32_16x16x32_bf16 v[8:11], v[210:213], v[186:189], v[8:11]
	v_mfma_f32_16x16x32_bf16 v[4:7], v[202:205], v[194:197], v[4:7]
	v_mfma_f32_16x16x32_bf16 v[0:3], v[210:213], v[194:197], v[0:3]
	v_mfma_f32_16x16x32_bf16 v[44:47], v[206:209], v[174:177], v[44:47]
	v_mfma_f32_16x16x32_bf16 v[40:43], v[216:219], v[174:177], v[40:43]
	v_mfma_f32_16x16x32_bf16 v[28:31], v[206:209], v[182:185], v[28:31]
	v_mfma_f32_16x16x32_bf16 v[24:27], v[216:219], v[182:185], v[24:27]
	v_mfma_f32_16x16x32_bf16 v[12:15], v[206:209], v[190:193], v[12:15]
	v_mfma_f32_16x16x32_bf16 v[8:11], v[216:219], v[190:193], v[8:11]
	v_mfma_f32_16x16x32_bf16 v[4:7], v[206:209], v[198:201], v[4:7]
	v_mfma_f32_16x16x32_bf16 v[0:3], v[216:219], v[198:201], v[0:3]
	s_barrier
	v_add_u32_e32 v252, 0x18000, v145
	v_add_u32_e32 v172, 0x1c000, v145
	ds_read_b128 v[150:153], v252
	ds_read_b128 v[154:157], v252 offset:1024
	ds_read_b128 v[158:161], v252 offset:2048
	ds_read_b128 v[162:165], v252 offset:3072
	ds_read_b128 v[166:169], v148 offset:32768
	ds_read_b128 v[174:177], v148 offset:33792
	ds_read_b128 v[178:181], v148 offset:34816
	ds_read_b128 v[182:185], v148 offset:35840
	ds_read_b128 v[186:189], v148 offset:36864
	ds_read_b128 v[190:193], v148 offset:37888
	ds_read_b128 v[194:197], v148 offset:38912
	ds_read_b128 v[198:201], v148 offset:39936
	s_waitcnt lgkmcnt(11)
	ds_read_b128 v[202:205], v172
	ds_read_b128 v[206:209], v172 offset:1024
	ds_read_b128 v[210:213], v172 offset:2048
	ds_read_b128 v[216:219], v172 offset:3072
	s_add_u32 s0, s56, 0x80000
	s_addc_u32 s1, s57, 0
	v_lshl_add_u64 v[238:239], s[0:1], 0, v[134:135]
	s_mov_b32 m0, s68
	s_nop 0
	global_load_lds_dwordx4 v[238:239], off
	v_lshl_add_u64 v[238:239], s[0:1], 0, v[130:131]
	s_mov_b32 m0, s69
	s_nop 0
	global_load_lds_dwordx4 v[238:239], off
	s_waitcnt lgkmcnt(0)
	s_mov_b32 s99, 0
	s_waitcnt vmcnt(8)
	s_barrier
	v_mfma_f32_16x16x32_bf16 v[124:127], v[150:153], v[166:169], v[124:127]
	v_mfma_f32_16x16x32_bf16 v[120:123], v[158:161], v[166:169], v[120:123]
	v_mfma_f32_16x16x32_bf16 v[116:119], v[150:153], v[178:181], v[116:119]
	v_mfma_f32_16x16x32_bf16 v[112:115], v[158:161], v[178:181], v[112:115]
	v_mfma_f32_16x16x32_bf16 v[100:103], v[150:153], v[186:189], v[100:103]
	v_mfma_f32_16x16x32_bf16 v[96:99], v[158:161], v[186:189], v[96:99]
	v_mfma_f32_16x16x32_bf16 v[84:87], v[150:153], v[194:197], v[84:87]
	v_mfma_f32_16x16x32_bf16 v[80:83], v[158:161], v[194:197], v[80:83]
	v_mfma_f32_16x16x32_bf16 v[124:127], v[154:157], v[174:177], v[124:127]
	v_mfma_f32_16x16x32_bf16 v[120:123], v[162:165], v[174:177], v[120:123]
	v_mfma_f32_16x16x32_bf16 v[116:119], v[154:157], v[182:185], v[116:119]
	v_mfma_f32_16x16x32_bf16 v[112:115], v[162:165], v[182:185], v[112:115]
	v_mfma_f32_16x16x32_bf16 v[100:103], v[154:157], v[190:193], v[100:103]
	v_mfma_f32_16x16x32_bf16 v[96:99], v[162:165], v[190:193], v[96:99]
	v_mfma_f32_16x16x32_bf16 v[84:87], v[154:157], v[198:201], v[84:87]
	v_mfma_f32_16x16x32_bf16 v[80:83], v[162:165], v[198:201], v[80:83]
	v_mfma_f32_16x16x32_bf16 v[108:111], v[202:205], v[166:169], v[108:111]
	v_mfma_f32_16x16x32_bf16 v[104:107], v[210:213], v[166:169], v[104:107]
	v_mfma_f32_16x16x32_bf16 v[92:95], v[202:205], v[178:181], v[92:95]
	v_mfma_f32_16x16x32_bf16 v[88:91], v[210:213], v[178:181], v[88:91]
	v_mfma_f32_16x16x32_bf16 v[76:79], v[202:205], v[186:189], v[76:79]
	v_mfma_f32_16x16x32_bf16 v[72:75], v[210:213], v[186:189], v[72:75]
	v_mfma_f32_16x16x32_bf16 v[68:71], v[202:205], v[194:197], v[68:71]
	v_mfma_f32_16x16x32_bf16 v[64:67], v[210:213], v[194:197], v[64:67]
	v_mfma_f32_16x16x32_bf16 v[108:111], v[206:209], v[174:177], v[108:111]
	v_mfma_f32_16x16x32_bf16 v[104:107], v[216:219], v[174:177], v[104:107]
	v_mfma_f32_16x16x32_bf16 v[92:95], v[206:209], v[182:185], v[92:95]
	v_mfma_f32_16x16x32_bf16 v[88:91], v[216:219], v[182:185], v[88:91]
	v_mfma_f32_16x16x32_bf16 v[76:79], v[206:209], v[190:193], v[76:79]
	v_mfma_f32_16x16x32_bf16 v[72:75], v[216:219], v[190:193], v[72:75]
	v_mfma_f32_16x16x32_bf16 v[68:71], v[206:209], v[198:201], v[68:71]
	v_mfma_f32_16x16x32_bf16 v[64:67], v[216:219], v[198:201], v[64:67]
	s_barrier
; #define PG8_STAGE(bufoff, gbase, voff) do { _Pragma("unroll") for (int _i = 0; _i < 2; ++_i) \
;         __builtin_amdgcn_global_load_lds((const unsigned*)((const char*)(gbase) + (voff)[_i]), (LAS unsigned*)(lds + (bufoff) + ldsw + _i * 8192), 16, 0, 0); } while (0)
; #define PG8_LDA(dst, b, h) do { _Pragma("unroll") for (int m = 0; m < 4; ++m) _Pragma("unroll") for (int k = 0; k < 2; ++k) dst[m][k] = *(const LAS bf16x8*)(lds + PG8_SA(b, h) + aoff + m * 2048 + k * 1024); } while (0)
; #define PG8_LDB(dst, b, h) do { _Pragma("unroll") for (int n = 0; n < 2; ++n) _Pragma("unroll") for (int k = 0; k < 2; ++k) dst[n][k] = *(const LAS bf16x8*)(lds + PG8_SB(b, h) + boff + n * 2048 + k * 1024); } while (0)
; #define PG8_MMA(ai, bj, At, Bt) do { __builtin_amdgcn_s_setprio(1); _Pragma("unroll") for (int m = 0; m < 4; ++m) _Pragma("unroll") for (int n = 0; n < 2; ++n) _Pragma("unroll") for (int k = 0; k < 2; ++k) \
;         acc[ai][bj][m][n] = __builtin_amdgcn_mfma_f32_16x16x32_bf16(Bt[n][k], At[m][k], acc[ai][bj][m][n], 0, 0, 0); __builtin_amdgcn_s_setprio(0); } while (0)
; #define PG8_WAIT_V(n) asm volatile("s_waitcnt vmcnt(" #n ")" ::: "memory")
; #define PG8_WAIT_L(n) asm volatile("s_waitcnt lgkmcnt(" #n ")" ::: "memory")
; #define PG8_BAR __builtin_amdgcn_s_barrier()
; #define PG8_SCHED __builtin_amdgcn_sched_barrier(0)
; template <class Epi>
; DI void gemm_phase(LAS unsigned char* lds, const Gemm g, const StaticOrder& S, const Epi& E) {
;     ...
;             PG8_LDB(B1, 1, 1); PG8_STAGE(PG8_SB(1, 0), b3, voffB);
;             PG8_BAR; PG8_WAIT_L(0); PG8_MMA(0, 1, At, B1); PG8_BAR;
;             PG8_LDA(At, 1, 1); PG8_STAGE(PG8_SA(1, 0), a3, voffA);
;             PG8_BAR; PG8_WAIT_L(0); PG8_MMA(1, 0, At, B0); PG8_BAR; PG8_SCHED;
;             PG8_STAGE(PG8_SB(1, 1), b3 + hstepB, voffB);
;             PG8_WAIT_V(6); PG8_BAR; PG8_MMA(1, 1, At, B1); PG8_BAR;
;         }
	ds_read_b128 v[166:169], v148 offset:49152
	ds_read_b128 v[174:177], v148 offset:50176
	ds_read_b128 v[178:181], v148 offset:51200
	ds_read_b128 v[182:185], v148 offset:52224
	ds_read_b128 v[186:189], v148 offset:53248
	ds_read_b128 v[190:193], v148 offset:54272
	ds_read_b128 v[194:197], v148 offset:55296
	ds_read_b128 v[198:201], v148 offset:56320
	s_add_i32 s0, s58, 0x18000
	v_lshl_add_u64 v[238:239], v[170:171], 0, s[4:5]
	s_mov_b32 m0, s0
	s_nop 0
	global_load_lds_dwordx4 v[238:239], off
	v_lshl_add_u64 v[238:239], v[220:221], 0, s[4:5]
	s_add_i32 m0, s0, 0x2000
	s_nop 0
	global_load_lds_dwordx4 v[238:239], off
	v_lshl_add_u64 v[238:239], v[222:223], 0, s[4:5]
	s_mov_b32 m0, s71
	s_nop 0
	global_load_lds_dwordx4 v[238:239], off
	v_lshl_add_u64 v[238:239], v[224:225], 0, s[4:5]
	s_mov_b32 m0, s72
	s_nop 0
	global_load_lds_dwordx4 v[238:239], off
	s_add_u32 s0, s54, 0x80080
	s_addc_u32 s1, s55, 0
	s_add_i32 s84, s58, 0x1c000
	v_lshl_add_u64 v[238:239], s[0:1], 0, v[132:133]
	s_mov_b32 m0, s84
	s_nop 0
	global_load_lds_dwordx4 v[238:239], off
	v_lshl_add_u64 v[238:239], s[0:1], 0, v[128:129]
	s_add_i32 m0, s84, 0x2000
	s_nop 0
	global_load_lds_dwordx4 v[238:239], off
	s_waitcnt lgkmcnt(0)
	s_waitcnt vmcnt(8)
	s_add_i32 s83, s83, 2
	s_add_u32 s52, s52, 0x100
	s_addc_u32 s53, s53, 0
	s_add_u32 s81, s81, 0x100
	s_addc_u32 s82, s82, 0
	s_cmp_gt_u32 s83, 29
	s_barrier
	v_mfma_f32_16x16x32_bf16 v[60:63], v[150:153], v[166:169], v[60:63]
	v_mfma_f32_16x16x32_bf16 v[56:59], v[158:161], v[166:169], v[56:59]
	v_mfma_f32_16x16x32_bf16 v[52:55], v[150:153], v[178:181], v[52:55]
	v_mfma_f32_16x16x32_bf16 v[48:51], v[158:161], v[178:181], v[48:51]
	v_mfma_f32_16x16x32_bf16 v[36:39], v[150:153], v[186:189], v[36:39]
	v_mfma_f32_16x16x32_bf16 v[32:35], v[158:161], v[186:189], v[32:35]
	v_mfma_f32_16x16x32_bf16 v[20:23], v[150:153], v[194:197], v[20:23]
	v_mfma_f32_16x16x32_bf16 v[16:19], v[158:161], v[194:197], v[16:19]
	v_mfma_f32_16x16x32_bf16 v[60:63], v[154:157], v[174:177], v[60:63]
	v_mfma_f32_16x16x32_bf16 v[56:59], v[162:165], v[174:177], v[56:59]
	v_mfma_f32_16x16x32_bf16 v[52:55], v[154:157], v[182:185], v[52:55]
	v_mfma_f32_16x16x32_bf16 v[48:51], v[162:165], v[182:185], v[48:51]
	v_mfma_f32_16x16x32_bf16 v[36:39], v[154:157], v[190:193], v[36:39]
	v_mfma_f32_16x16x32_bf16 v[32:35], v[162:165], v[190:193], v[32:35]
	v_mfma_f32_16x16x32_bf16 v[20:23], v[154:157], v[198:201], v[20:23]
	v_mfma_f32_16x16x32_bf16 v[16:19], v[162:165], v[198:201], v[16:19]
	v_mfma_f32_16x16x32_bf16 v[44:47], v[202:205], v[166:169], v[44:47]
	v_mfma_f32_16x16x32_bf16 v[40:43], v[210:213], v[166:169], v[40:43]
	v_mfma_f32_16x16x32_bf16 v[28:31], v[202:205], v[178:181], v[28:31]
	v_mfma_f32_16x16x32_bf16 v[24:27], v[210:213], v[178:181], v[24:27]
	v_mfma_f32_16x16x32_bf16 v[12:15], v[202:205], v[186:189], v[12:15]
	v_mfma_f32_16x16x32_bf16 v[8:11], v[210:213], v[186:189], v[8:11]
	v_mfma_f32_16x16x32_bf16 v[4:7], v[202:205], v[194:197], v[4:7]
	v_mfma_f32_16x16x32_bf16 v[0:3], v[210:213], v[194:197], v[0:3]
	v_mfma_f32_16x16x32_bf16 v[44:47], v[206:209], v[174:177], v[44:47]
	v_mfma_f32_16x16x32_bf16 v[40:43], v[216:219], v[174:177], v[40:43]
	v_mfma_f32_16x16x32_bf16 v[28:31], v[206:209], v[182:185], v[28:31]
	v_mfma_f32_16x16x32_bf16 v[24:27], v[216:219], v[182:185], v[24:27]
	v_mfma_f32_16x16x32_bf16 v[12:15], v[206:209], v[190:193], v[12:15]
	v_mfma_f32_16x16x32_bf16 v[8:11], v[216:219], v[190:193], v[8:11]
	v_mfma_f32_16x16x32_bf16 v[4:7], v[206:209], v[198:201], v[4:7]
	v_mfma_f32_16x16x32_bf16 v[0:3], v[216:219], v[198:201], v[0:3]
	s_barrier
	s_cbranch_scc0 .LBB0_113
; DI unsigned pk2(float lo, float hi) { f32x2 v = {lo, hi}; bf16x2_t b = __builtin_convertvector(v, bf16x2_t); return __builtin_bit_cast(unsigned, b); }
; template <class Epi>
; DI void gemm_phase(LAS unsigned char* lds, const Gemm g, const StaticOrder& S, const Epi& E) {
;     ...
;         E(acc, cur, wr, wc, fr, fq);
;         if (!has_next) break;
; #pragma unroll
;         for (int a = 0; a < 2; ++a)
; #pragma unroll
;             for (int b = 0; b < 2; ++b)
; #pragma unroll
;                 for (int m = 0; m < 4; ++m)
; #pragma unroll
;                     for (int n = 0; n < 2; ++n) acc[a][b][m][n] = (f32x4){0.f, 0.f, 0.f, 0.f};
;         cur = nxt; cA = nA; cB = nB; ++ui;
;     DI void operator()(const f32x4 (&acc)[2][2][4][2], const Unit& u, int wr, int wc, int fr, int fq) const {
;         const int row0 = u.pm * BM + wr * 64 + fr, col0 = u.pn * BM + wc * 32 + 8 * fq;
; #pragma unroll
;         for (int ai = 0; ai < 2; ++ai)
; #pragma unroll
;             for (int m = 0; m < 4; ++m) { bf16_t* rowp = O + (size_t)(row0 + ai * HALF + m * 16) * ldc + col0;
; #pragma unroll
;                 for (int bj = 0; bj < 2; ++bj) { const f32x4 v0 = acc[ai][bj][m][0], v1 = acc[ai][bj][m][1];
;                     u32x4 w; w.x = pk2(v0[0], v0[1]); w.y = pk2(v0[2], v0[3]); w.z = pk2(v1[0], v1[1]); w.w = pk2(v1[2], v1[3]);
;                     *(u32x4*)(rowp + bj * HALF) = w; } }
	v_lshl_add_u32 v156, s8, 8, v144
	v_lshl_or_b32 v150, s78, 8, v146
	v_ashrrev_i32_e32 v151, 31, v150
	v_mov_b64_e32 v[152:153], s[30:31]
	v_cvt_pk_bf16_f32 v68, v68, v69
	v_cvt_pk_bf16_f32 v69, v70, v71
	v_cvt_pk_bf16_f32 v70, v64, v65
	v_add_u32_e32 v64, 0x80, v156
	v_mad_i64_i32 v[154:155], s[0:1], v156, s77, v[152:153]
	v_lshlrev_b64 v[150:151], 1, v[150:151]
	v_cvt_pk_bf16_f32 v108, v108, v109
	v_cvt_pk_bf16_f32 v109, v110, v111
	v_cvt_pk_bf16_f32 v110, v104, v105
	v_or_b32_e32 v104, 16, v156
	v_mad_i64_i32 v[64:65], s[0:1], v64, s77, v[152:153]
	v_cvt_pk_bf16_f32 v44, v44, v45
	v_cvt_pk_bf16_f32 v45, v46, v47
	v_cvt_pk_bf16_f32 v46, v40, v41
	v_add_u32_e32 v40, 0x90, v156
	v_lshl_add_u64 v[154:155], v[154:155], 0, v[150:151]
	v_cvt_pk_bf16_f32 v111, v106, v107
	v_mad_i64_i32 v[104:105], s[0:1], v104, s77, v[152:153]
	v_cvt_pk_bf16_f32 v92, v92, v93
	v_cvt_pk_bf16_f32 v93, v94, v95
	v_cvt_pk_bf16_f32 v94, v88, v89
	v_or_b32_e32 v88, 32, v156
	v_lshl_add_u64 v[64:65], v[64:65], 0, v[150:151]
	v_cvt_pk_bf16_f32 v47, v42, v43
	v_mad_i64_i32 v[40:41], s[0:1], v40, s77, v[152:153]
	v_cvt_pk_bf16_f32 v28, v28, v29
	v_cvt_pk_bf16_f32 v29, v30, v31
	v_cvt_pk_bf16_f32 v30, v24, v25
	v_add_u32_e32 v24, 0xa0, v156
	global_store_dwordx4 v[154:155], v[108:111], off offset:256 nt
	v_cvt_pk_bf16_f32 v95, v90, v91
	v_mad_i64_i32 v[88:89], s[0:1], v88, s77, v[152:153]
	v_lshl_add_u64 v[108:109], v[104:105], 0, v[150:151]
	v_cvt_pk_bf16_f32 v76, v76, v77
	v_cvt_pk_bf16_f32 v77, v78, v79
	v_cvt_pk_bf16_f32 v78, v72, v73
	v_or_b32_e32 v72, 48, v156
	global_store_dwordx4 v[64:65], v[44:47], off offset:256 nt
	v_cvt_pk_bf16_f32 v31, v26, v27
	v_mad_i64_i32 v[24:25], s[0:1], v24, s77, v[152:153]
	v_lshl_add_u64 v[44:45], v[40:41], 0, v[150:151]
	v_cvt_pk_bf16_f32 v12, v12, v13
	v_cvt_pk_bf16_f32 v13, v14, v15
	v_cvt_pk_bf16_f32 v14, v8, v9
	v_add_u32_e32 v8, 0xb0, v156
	global_store_dwordx4 v[108:109], v[92:95], off offset:256 nt
	v_cvt_pk_bf16_f32 v79, v74, v75
	v_mad_i64_i32 v[72:73], s[0:1], v72, s77, v[152:153]
	v_lshl_add_u64 v[92:93], v[88:89], 0, v[150:151]
	global_store_dwordx4 v[44:45], v[28:31], off offset:256 nt
	v_cvt_pk_bf16_f32 v15, v10, v11
	v_mad_i64_i32 v[8:9], s[0:1], v8, s77, v[152:153]
	v_lshl_add_u64 v[28:29], v[24:25], 0, v[150:151]
	v_cvt_pk_bf16_f32 v124, v124, v125
	v_cvt_pk_bf16_f32 v125, v126, v127
	v_cvt_pk_bf16_f32 v126, v120, v121
	v_cvt_pk_bf16_f32 v127, v122, v123
	v_cvt_pk_bf16_f32 v104, v116, v117
	v_cvt_pk_bf16_f32 v105, v118, v119
	v_cvt_pk_bf16_f32 v106, v112, v113
	v_cvt_pk_bf16_f32 v107, v114, v115
	v_cvt_pk_bf16_f32 v88, v100, v101
	v_cvt_pk_bf16_f32 v89, v102, v103
	v_cvt_pk_bf16_f32 v90, v96, v97
	v_cvt_pk_bf16_f32 v91, v98, v99
	global_store_dwordx4 v[92:93], v[76:79], off offset:256 nt
	v_cvt_pk_bf16_f32 v74, v80, v81
	v_cvt_pk_bf16_f32 v75, v82, v83
	v_lshl_add_u64 v[76:77], v[72:73], 0, v[150:151]
	v_cvt_pk_bf16_f32 v72, v84, v85
	v_cvt_pk_bf16_f32 v73, v86, v87
	v_cvt_pk_bf16_f32 v71, v66, v67
	v_cvt_pk_bf16_f32 v60, v60, v61
	v_cvt_pk_bf16_f32 v61, v62, v63
	v_cvt_pk_bf16_f32 v62, v56, v57
	v_cvt_pk_bf16_f32 v63, v58, v59
	v_cvt_pk_bf16_f32 v40, v52, v53
	v_cvt_pk_bf16_f32 v41, v54, v55
	v_cvt_pk_bf16_f32 v42, v48, v49
	v_cvt_pk_bf16_f32 v43, v50, v51
	v_cvt_pk_bf16_f32 v24, v36, v37
	v_cvt_pk_bf16_f32 v25, v38, v39
	v_cvt_pk_bf16_f32 v26, v32, v33
	v_cvt_pk_bf16_f32 v27, v34, v35
	global_store_dwordx4 v[28:29], v[12:15], off offset:256 nt
	v_cvt_pk_bf16_f32 v10, v16, v17
	v_cvt_pk_bf16_f32 v11, v18, v19
	v_lshl_add_u64 v[12:13], v[8:9], 0, v[150:151]
	v_cvt_pk_bf16_f32 v8, v20, v21
	v_cvt_pk_bf16_f32 v9, v22, v23
	v_cvt_pk_bf16_f32 v4, v4, v5
	v_cvt_pk_bf16_f32 v5, v6, v7
	v_cvt_pk_bf16_f32 v6, v0, v1
	v_cvt_pk_bf16_f32 v7, v2, v3
	s_and_b64 vcc, exec, s[2:3]
	s_mov_b32 s78, s16
	s_mov_b32 s8, s46
	s_mov_b64 s[54:55], s[50:51]
	s_mov_b64 s[52:53], s[48:49]
	global_store_dwordx4 v[154:155], v[124:127], off nt
	global_store_dwordx4 v[108:109], v[104:107], off nt
	global_store_dwordx4 v[92:93], v[88:91], off nt
	global_store_dwordx4 v[76:77], v[72:75], off nt
	global_store_dwordx4 v[76:77], v[68:71], off offset:256 nt
	global_store_dwordx4 v[64:65], v[60:63], off nt
	global_store_dwordx4 v[44:45], v[40:43], off nt
	global_store_dwordx4 v[28:29], v[24:27], off nt
	global_store_dwordx4 v[12:13], v[8:11], off nt
	global_store_dwordx4 v[12:13], v[4:7], off offset:256 nt
	s_mov_b32 s98, 1
	s_cbranch_vccz .LBB0_110
	s_waitcnt vmcnt(0)
	s_cmpk_gt_u32 s33, 0xff
	s_cbranch_scc1 .LBB0_117
	s_barrier
